# residual GEMM epilogue de-serialised: the four {4 loads, wait, use} groups of the x read-modify-write issue 12 loads up front and the last 4 one group early (lever 2)
# baseline (speedup 1.0000x reference)
; __device__ __forceinline__ unsigned cvt_pk_bf16(float lo, float hi) { unsigned r; asm("v_cvt_pk_bf16_f32 %0, %1, %2" : "=v"(r) : "v"(lo), "v"(hi)); return r; }
;     __device__ __forceinline__ void operator()(const f32x4 (&acc)[2][2][4][2], const Unit& u, int wr, int wc, int fr, int fq) const {
;     ...
;             for (int am = 0; am < 4; ++am) { const int ai = am >> 1, mb = (am & 1) * 2;
;                 v4u xv[2][2];
; #pragma unroll
;                 for (int mm = 0; mm < 2; ++mm) { const int m = mb + mm; const bf16* rp = (const bf16*)(ws + WS_XB) + (size_t)(row0 + ai * 128 + m * 16) * D + colw;
; #pragma unroll
;                     for (int bj = 0; bj < 2; ++bj) xv[mm][bj] = *(const v4u*)(rp + bj * 128); }
; #pragma unroll
;                 for (int mm = 0; mm < 2; ++mm) { const int m = mb + mm;
;                     const int row = row0 + ai * 128 + m * 16;
;                     bf16* xb = (bf16*)(ws + WS_XB) + (size_t)row * D + colw;
;                     float ssq = 0.f;
; #pragma unroll
;                     for (int bj = 0; bj < 2; ++bj) {
;                         const auto s0 = __builtin_amdgcn_permlane16_swap(xv[mm][bj].x, xv[mm][bj].z, false, false), s1 = __builtin_amdgcn_permlane16_swap(xv[mm][bj].y, xv[mm][bj].w, false, false);
;                         const unsigned xn[2][2] = {{s0[0], s1[0]}, {s0[1], s1[1]}};
;                         unsigned wn[2][2];
; #pragma unroll
;                         for (int n = 0; n < 2; ++n) {
;                             const f32x4 v = (f32x4){bf_lo(xn[n][0]), bf_hi(xn[n][0]), bf_lo(xn[n][1]), bf_hi(xn[n][1])} + acc[ai][bj][m][n] * amul;
;                             wn[n][0] = cvt_pk_bf16(v.x, v.y); wn[n][1] = cvt_pk_bf16(v.z, v.w);
;                             if (slot >= 0) ssq += (v.x * v.x + v.y * v.y) + (v.z * v.z + v.w * v.w); }
;                         const auto t0 = __builtin_amdgcn_permlane16_swap(wn[0][0], wn[1][0], false, false), t1 = __builtin_amdgcn_permlane16_swap(wn[0][1], wn[1][1], false, false);
;                         *(v4u*)(xb + bj * 128) = (v4u){t0[0], t1[0], t0[1], t1[1]};
;                     }
;                     if (slot >= 0) { ssq += shfl_xor_l(ssq, 16, fq * 16 + fr); ssq += shfl_xor_l(ssq, 32, fq * 16 + fr); if (fq == 0) ((float*)(ws + WS_SS))[((size_t)slot * M + row) * 16 + u.pn * 4 + wc] = ssq; }
.LBB0_851:
	v_lshl_or_b32 v138, s87, 8, v244
	v_ashrrev_i32_e32 v139, 31, v138
	v_lshlrev_b64 v[150:151], 1, v[138:139]
	v_ashrrev_i32_e32 v211, 31, v210
	v_lshl_add_u64 v[140:141], s[90:91], 0, v[150:151]
	v_lshlrev_b64 v[152:153], 11, v[210:211]
	s_waitcnt lgkmcnt(0)
	v_lshl_add_u64 v[130:131], v[140:141], 0, v[152:153]
	v_add_u32_e32 v221, v152, v150
	global_load_dwordx4 v[170:173], v221, s[90:91]
	global_load_dwordx4 v[174:177], v221, s[90:91] offset:256
	s_nop 0
	v_add_u32_e32 v234, 0x8000, v221
	global_load_dwordx4 v[178:181], v234, s[90:91]
	global_load_dwordx4 v[182:185], v234, s[90:91] offset:256
	s_nop 0
	v_add_u32_e32 v234, 0x10000, v221
	global_load_dwordx4 v[186:189], v234, s[90:91]
	global_load_dwordx4 v[190:193], v234, s[90:91] offset:256
	s_nop 0
	v_add_u32_e32 v234, 0x18000, v221
	global_load_dwordx4 v[196:199], v234, s[90:91]
	global_load_dwordx4 v[200:203], v234, s[90:91] offset:256
	s_nop 0
	v_add_u32_e32 v234, 0x40000, v221
	global_load_dwordx4 v[204:207], v234, s[90:91]
	global_load_dwordx4 v[212:215], v234, s[90:91] offset:256
	s_nop 0
	v_add_u32_e32 v234, 0x48000, v221
	global_load_dwordx4 v[216:219], v234, s[90:91]
	global_load_dwordx4 v[246:249], v234, s[90:91] offset:256
	s_nop 0
	v_or_b32_e32 v142, 16, v210
	v_ashrrev_i32_e32 v143, 31, v142
	v_lshlrev_b64 v[144:145], 11, v[142:143]
	v_lshl_add_u64 v[130:131], v[140:141], 0, v[144:145]
	s_nop 0
	v_lshl_add_u64 v[152:153], s[90:91], 0, v[152:153]
	v_lshl_add_u64 v[166:167], v[152:153], 0, v[150:151]
	s_andn2_b64 vcc, exec, s[36:37]
	s_waitcnt vmcnt(8)
	v_mov_b32_e32 v146, v170
	v_mov_b32_e32 v147, v171
	v_mov_b32_e32 v148, v172
	v_mov_b32_e32 v149, v173
	v_mov_b32_e32 v154, v174
	v_mov_b32_e32 v155, v175
	v_mov_b32_e32 v156, v176
	v_mov_b32_e32 v157, v177
	v_mov_b32_e32 v134, v178
	v_mov_b32_e32 v135, v179
	v_mov_b32_e32 v136, v180
	v_mov_b32_e32 v137, v181
	v_mov_b32_e32 v130, v182
	v_mov_b32_e32 v131, v183
	v_mov_b32_e32 v132, v184
	v_mov_b32_e32 v133, v185
	v_mov_b32_e32 v0, v148
	s_nop 1
	v_permlane16_swap_b32_e32 v146, v0
	v_mov_b32_e32 v160, v149
	s_nop 1
	v_permlane16_swap_b32_e32 v147, v160
	v_lshlrev_b32_e32 v148, 16, v146
	v_and_b32_e32 v149, 0xffff0000, v146
	v_lshlrev_b32_e32 v146, 16, v147
	v_and_b32_e32 v147, 0xffff0000, v147
	v_pk_add_f32 v[150:151], v[122:123], v[148:149]
	v_lshlrev_b32_e32 v152, 16, v0
	v_and_b32_e32 v153, 0xffff0000, v0
	v_lshlrev_b32_e32 v148, 16, v160
	v_and_b32_e32 v149, 0xffff0000, v160
	v_mov_b32_e32 v0, v156
	v_pk_add_f32 v[146:147], v[124:125], v[146:147]
	v_cvt_pk_bf16_f32 v158, v150, v151
	v_pk_add_f32 v[148:149], v[116:117], v[148:149]
	v_cvt_pk_bf16_f32 v159, v146, v147
	v_pk_add_f32 v[152:153], v[114:115], v[152:153]
	v_cvt_pk_bf16_f32 v161, v148, v149
	v_permlane16_swap_b32_e32 v154, v0
	v_cvt_pk_bf16_f32 v160, v152, v153
	v_mov_b32_e32 v164, v157
	v_permlane16_swap_b32_e32 v158, v160
	v_permlane16_swap_b32_e32 v159, v161
	v_permlane16_swap_b32_e32 v155, v164
	v_lshlrev_b32_e32 v156, 16, v154
	v_and_b32_e32 v157, 0xffff0000, v154
	global_store_dwordx4 v[166:167], v[158:161], off
	v_lshlrev_b32_e32 v154, 16, v155
	v_and_b32_e32 v155, 0xffff0000, v155
	v_pk_add_f32 v[158:159], v[126:127], v[156:157]
	v_lshlrev_b32_e32 v160, 16, v0
	v_and_b32_e32 v161, 0xffff0000, v0
	v_lshlrev_b32_e32 v156, 16, v164
	v_and_b32_e32 v157, 0xffff0000, v164
	v_pk_add_f32 v[154:155], v[128:129], v[154:155]
	v_cvt_pk_bf16_f32 v162, v158, v159
	v_pk_add_f32 v[156:157], v[120:121], v[156:157]
	v_cvt_pk_bf16_f32 v163, v154, v155
	v_pk_add_f32 v[160:161], v[118:119], v[160:161]
	v_cvt_pk_bf16_f32 v165, v156, v157
	v_cndmask_b32_e64 v0, 0, 1, s[36:37]
	v_cvt_pk_bf16_f32 v164, v160, v161
	v_permlane16_swap_b32_e32 v163, v165
	v_permlane16_swap_b32_e32 v162, v164
	v_cmp_ne_u32_e64 s[10:11], 1, v0
	global_store_dwordx4 v[166:167], v[162:165], off offset:256
	s_cbranch_vccnz .LBB0_855
	v_mul_f32_e32 v0, v151, v151
	v_mul_f32_e32 v147, v147, v147
	v_fmac_f32_e32 v0, v150, v150
	v_fmac_f32_e32 v147, v146, v146
	v_add_f32_e32 v0, v0, v147
	v_mul_f32_e32 v146, v153, v153
	v_mul_f32_e32 v147, v149, v149
	v_fmac_f32_e32 v146, v152, v152
	v_fmac_f32_e32 v147, v148, v148
	v_add_f32_e32 v146, v146, v147
	v_add_f32_e32 v0, v0, v146
	v_mul_f32_e32 v146, v159, v159
	v_mul_f32_e32 v147, v155, v155
	v_fmac_f32_e32 v146, v158, v158
	v_fmac_f32_e32 v147, v154, v154
	v_add_f32_e32 v146, v146, v147
	v_add_f32_e32 v0, v0, v146
	v_mul_f32_e32 v146, v161, v161
	v_mul_f32_e32 v147, v157, v157
	v_fmac_f32_e32 v146, v160, v160
	v_fmac_f32_e32 v147, v156, v156
	v_add_f32_e32 v146, v146, v147
	v_add_f32_e32 v0, v146, v0
	ds_bpermute_b32 v146, v241, v0
	s_waitcnt lgkmcnt(0)
	v_add_f32_e32 v0, v0, v146
	ds_bpermute_b32 v146, v242, v0
	s_and_saveexec_b64 s[0:1], s[6:7]
	s_cbranch_execz .LBB0_854
	s_waitcnt lgkmcnt(0)
	v_add_f32_e32 v0, v0, v146
	v_lshl_add_u64 v[146:147], s[38:39], 0, v[210:211]
	v_readlane_b32 s18, v252, 23
	s_lshl_b32 s2, s87, 2
	v_lshlrev_b64 v[146:147], 6, v[146:147]
	v_readlane_b32 s19, v252, 24
	s_ashr_i32 s3, s2, 31
	s_lshl_b32 s94, s65, 2
	v_lshl_add_u64 v[146:147], s[18:19], 0, v[146:147]
	v_lshl_add_u64 v[146:147], s[2:3], 2, v[146:147]
	v_lshl_add_u64 v[146:147], v[146:147], 0, s[94:95]
	global_store_dword v[146:147], v0, off

; __device__ __forceinline__ unsigned cvt_pk_bf16(float lo, float hi) { unsigned r; asm("v_cvt_pk_bf16_f32 %0, %1, %2" : "=v"(r) : "v"(lo), "v"(hi)); return r; }
;     __device__ __forceinline__ void operator()(const f32x4 (&acc)[2][2][4][2], const Unit& u, int wr, int wc, int fr, int fq) const {
;     ...
;             for (int am = 0; am < 4; ++am) { const int ai = am >> 1, mb = (am & 1) * 2;
;                 v4u xv[2][2];
; #pragma unroll
;                 for (int mm = 0; mm < 2; ++mm) { const int m = mb + mm; const bf16* rp = (const bf16*)(ws + WS_XB) + (size_t)(row0 + ai * 128 + m * 16) * D + colw;
; #pragma unroll
;                     for (int bj = 0; bj < 2; ++bj) xv[mm][bj] = *(const v4u*)(rp + bj * 128); }
; #pragma unroll
;                 for (int mm = 0; mm < 2; ++mm) { const int m = mb + mm;
;                     const int row = row0 + ai * 128 + m * 16;
;                     bf16* xb = (bf16*)(ws + WS_XB) + (size_t)row * D + colw;
;                     float ssq = 0.f;
; #pragma unroll
;                     for (int bj = 0; bj < 2; ++bj) {
;                         const auto s0 = __builtin_amdgcn_permlane16_swap(xv[mm][bj].x, xv[mm][bj].z, false, false), s1 = __builtin_amdgcn_permlane16_swap(xv[mm][bj].y, xv[mm][bj].w, false, false);
;                         const unsigned xn[2][2] = {{s0[0], s1[0]}, {s0[1], s1[1]}};
;                         unsigned wn[2][2];
; #pragma unroll
;                         for (int n = 0; n < 2; ++n) {
;                             const f32x4 v = (f32x4){bf_lo(xn[n][0]), bf_hi(xn[n][0]), bf_lo(xn[n][1]), bf_hi(xn[n][1])} + acc[ai][bj][m][n] * amul;
;                             wn[n][0] = cvt_pk_bf16(v.x, v.y); wn[n][1] = cvt_pk_bf16(v.z, v.w);
;                             if (slot >= 0) ssq += (v.x * v.x + v.y * v.y) + (v.z * v.z + v.w * v.w); }
;                         const auto t0 = __builtin_amdgcn_permlane16_swap(wn[0][0], wn[1][0], false, false), t1 = __builtin_amdgcn_permlane16_swap(wn[0][1], wn[1][1], false, false);
;                         *(v4u*)(xb + bj * 128) = (v4u){t0[0], t1[0], t0[1], t1[1]};
;                     }
;                     if (slot >= 0) { ssq += shfl_xor_l(ssq, 16, fq * 16 + fr); ssq += shfl_xor_l(ssq, 32, fq * 16 + fr); if (fq == 0) ((float*)(ws + WS_SS))[((size_t)slot * M + row) * 16 + u.pn * 4 + wc] = ssq; }
.LBB0_859:
	v_or_b32_e32 v146, 32, v210
	v_ashrrev_i32_e32 v147, 31, v146
	v_lshlrev_b64 v[152:153], 11, v[146:147]
	s_waitcnt lgkmcnt(0)
	v_lshl_add_u64 v[130:131], v[140:141], 0, v[152:153]
	v_add_u32_e32 v234, 0x50000, v221
	global_load_dwordx4 v[170:173], v234, s[90:91]
	global_load_dwordx4 v[174:177], v234, s[90:91] offset:256
	s_nop 0
	v_add_u32_e32 v234, 0x58000, v221
	global_load_dwordx4 v[178:181], v234, s[90:91]
	global_load_dwordx4 v[182:185], v234, s[90:91] offset:256
	s_nop 0
	v_or_b32_e32 v142, 48, v210
	v_ashrrev_i32_e32 v143, 31, v142
	v_lshlrev_b64 v[144:145], 11, v[142:143]
	v_lshl_add_u64 v[130:131], v[140:141], 0, v[144:145]
	s_nop 0
	v_lshl_add_u64 v[152:153], s[90:91], 0, v[152:153]
	v_lshl_add_u64 v[168:169], v[138:139], 1, v[152:153]
	s_and_b64 vcc, exec, s[10:11]
	s_waitcnt vmcnt(12)
	v_mov_b32_e32 v148, v186
	v_mov_b32_e32 v149, v187
	v_mov_b32_e32 v150, v188
	v_mov_b32_e32 v151, v189
	v_mov_b32_e32 v156, v190
	v_mov_b32_e32 v157, v191
	v_mov_b32_e32 v158, v192
	v_mov_b32_e32 v159, v193
	v_mov_b32_e32 v134, v196
	v_mov_b32_e32 v135, v197
	v_mov_b32_e32 v136, v198
	v_mov_b32_e32 v137, v199
	v_mov_b32_e32 v130, v200
	v_mov_b32_e32 v131, v201
	v_mov_b32_e32 v132, v202
	v_mov_b32_e32 v133, v203
	v_mov_b32_e32 v0, v150
	s_nop 1
	v_permlane16_swap_b32_e32 v148, v0
	v_mov_b32_e32 v162, v151
	s_nop 1
	v_permlane16_swap_b32_e32 v149, v162
	v_lshlrev_b32_e32 v150, 16, v148
	v_and_b32_e32 v151, 0xffff0000, v148
	v_lshlrev_b32_e32 v148, 16, v149
	v_and_b32_e32 v149, 0xffff0000, v149
	v_pk_add_f32 v[152:153], v[90:91], v[150:151]
	v_lshlrev_b32_e32 v154, 16, v0
	v_and_b32_e32 v155, 0xffff0000, v0
	v_lshlrev_b32_e32 v150, 16, v162
	v_and_b32_e32 v151, 0xffff0000, v162
	v_mov_b32_e32 v0, v158
	v_pk_add_f32 v[148:149], v[92:93], v[148:149]
	v_cvt_pk_bf16_f32 v160, v152, v153
	v_pk_add_f32 v[150:151], v[84:85], v[150:151]
	v_cvt_pk_bf16_f32 v161, v148, v149
	v_pk_add_f32 v[154:155], v[82:83], v[154:155]
	v_cvt_pk_bf16_f32 v163, v150, v151
	v_permlane16_swap_b32_e32 v156, v0
	v_cvt_pk_bf16_f32 v162, v154, v155
	v_mov_b32_e32 v166, v159
	v_permlane16_swap_b32_e32 v160, v162
	v_permlane16_swap_b32_e32 v161, v163
	v_permlane16_swap_b32_e32 v157, v166
	v_lshlrev_b32_e32 v158, 16, v156
	v_and_b32_e32 v159, 0xffff0000, v156
	global_store_dwordx4 v[168:169], v[160:163], off
	v_lshlrev_b32_e32 v156, 16, v157
	v_and_b32_e32 v157, 0xffff0000, v157
	v_pk_add_f32 v[160:161], v[94:95], v[158:159]
	v_lshlrev_b32_e32 v162, 16, v0
	v_and_b32_e32 v163, 0xffff0000, v0
	v_lshlrev_b32_e32 v158, 16, v166
	v_and_b32_e32 v159, 0xffff0000, v166
	v_pk_add_f32 v[156:157], v[96:97], v[156:157]
	v_cvt_pk_bf16_f32 v164, v160, v161
	v_pk_add_f32 v[158:159], v[88:89], v[158:159]
	v_cvt_pk_bf16_f32 v165, v156, v157
	v_pk_add_f32 v[162:163], v[86:87], v[162:163]
	v_cvt_pk_bf16_f32 v167, v158, v159
	s_nop 0
	v_cvt_pk_bf16_f32 v166, v162, v163
	v_permlane16_swap_b32_e32 v165, v167
	v_permlane16_swap_b32_e32 v164, v166
	global_store_dwordx4 v[168:169], v[164:167], off offset:256
	s_cbranch_vccnz .LBB0_863
	v_mul_f32_e32 v0, v153, v153
	v_mul_f32_e32 v149, v149, v149
	v_fmac_f32_e32 v0, v152, v152
	v_fmac_f32_e32 v149, v148, v148
	v_add_f32_e32 v0, v0, v149
	v_mul_f32_e32 v148, v155, v155
	v_mul_f32_e32 v149, v151, v151
	v_fmac_f32_e32 v148, v154, v154
	v_fmac_f32_e32 v149, v150, v150
	v_add_f32_e32 v148, v148, v149
	v_add_f32_e32 v0, v0, v148
	v_mul_f32_e32 v148, v161, v161
	v_mul_f32_e32 v149, v157, v157
	v_fmac_f32_e32 v148, v160, v160
	v_fmac_f32_e32 v149, v156, v156
	v_add_f32_e32 v148, v148, v149
	v_add_f32_e32 v0, v0, v148
	v_mul_f32_e32 v148, v163, v163
	v_mul_f32_e32 v149, v159, v159
	v_fmac_f32_e32 v148, v162, v162
	v_fmac_f32_e32 v149, v158, v158
	v_add_f32_e32 v148, v148, v149
	v_add_f32_e32 v0, v148, v0
	ds_bpermute_b32 v148, v241, v0
	s_waitcnt lgkmcnt(0)
	v_add_f32_e32 v0, v0, v148
	ds_bpermute_b32 v148, v242, v0
	s_and_saveexec_b64 s[0:1], s[6:7]
	s_cbranch_execz .LBB0_862
	v_lshl_add_u64 v[146:147], s[38:39], 0, v[146:147]
	v_readlane_b32 s18, v252, 23
	s_lshl_b32 s2, s87, 2
	v_lshlrev_b64 v[146:147], 6, v[146:147]
	v_readlane_b32 s19, v252, 24
	s_ashr_i32 s3, s2, 31
	s_lshl_b32 s94, s65, 2
	v_lshl_add_u64 v[146:147], s[18:19], 0, v[146:147]
	v_lshl_add_u64 v[146:147], s[2:3], 2, v[146:147]
	s_waitcnt lgkmcnt(0)
	v_add_f32_e32 v0, v0, v148
	v_lshl_add_u64 v[146:147], v[146:147], 0, s[94:95]
	global_store_dword v[146:147], v0, off

; __device__ __forceinline__ unsigned cvt_pk_bf16(float lo, float hi) { unsigned r; asm("v_cvt_pk_bf16_f32 %0, %1, %2" : "=v"(r) : "v"(lo), "v"(hi)); return r; }
; __device__ __forceinline__ float bf_lo(unsigned w) { return __uint_as_float(w << 16); }
; __device__ __forceinline__ float bf_hi(unsigned w) { return __uint_as_float(w & 0xffff0000u); }
; __device__ __forceinline__ float shfl_xor_l(float v, int m, int lane) { return __int_as_float(__builtin_amdgcn_ds_bpermute((lane ^ m) << 2, __float_as_int(v))); }
;     __device__ __forceinline__ void operator()(const f32x4 (&acc)[2][2][4][2], const Unit& u, int wr, int wc, int fr, int fq) const {
;     ...
;                 for (int mm = 0; mm < 2; ++mm) { const int m = mb + mm;
;                     const int row = row0 + ai * 128 + m * 16;
;                     bf16* xb = (bf16*)(ws + WS_XB) + (size_t)row * D + colw;
;                     float ssq = 0.f;
; #pragma unroll
;                     for (int bj = 0; bj < 2; ++bj) {
;                         const auto s0 = __builtin_amdgcn_permlane16_swap(xv[mm][bj].x, xv[mm][bj].z, false, false), s1 = __builtin_amdgcn_permlane16_swap(xv[mm][bj].y, xv[mm][bj].w, false, false);
;                         const unsigned xn[2][2] = {{s0[0], s1[0]}, {s0[1], s1[1]}};
;                         unsigned wn[2][2];
; #pragma unroll
;                         for (int n = 0; n < 2; ++n) {
;                             const f32x4 v = (f32x4){bf_lo(xn[n][0]), bf_hi(xn[n][0]), bf_lo(xn[n][1]), bf_hi(xn[n][1])} + acc[ai][bj][m][n] * amul;
;                             wn[n][0] = cvt_pk_bf16(v.x, v.y); wn[n][1] = cvt_pk_bf16(v.z, v.w);
;                             if (slot >= 0) ssq += (v.x * v.x + v.y * v.y) + (v.z * v.z + v.w * v.w); }
;                         const auto t0 = __builtin_amdgcn_permlane16_swap(wn[0][0], wn[1][0], false, false), t1 = __builtin_amdgcn_permlane16_swap(wn[0][1], wn[1][1], false, false);
;                         *(v4u*)(xb + bj * 128) = (v4u){t0[0], t1[0], t0[1], t1[1]};
;                     }
;                     if (slot >= 0) { ssq += shfl_xor_l(ssq, 16, fq * 16 + fr); ssq += shfl_xor_l(ssq, 32, fq * 16 + fr); if (fq == 0) ((float*)(ws + WS_SS))[((size_t)slot * M + row) * 16 + u.pn * 4 + wc] = ssq; }
.LBB0_863:
	v_lshl_add_u64 v[144:145], s[90:91], 0, v[144:145]
	v_lshl_add_u64 v[156:157], v[138:139], 1, v[144:145]
	v_mov_b32_e32 v0, v136
	v_mov_b32_e32 v145, v137
	s_nop 0
	v_permlane16_swap_b32_e32 v134, v0
	v_permlane16_swap_b32_e32 v135, v145
	v_lshlrev_b32_e32 v136, 16, v134
	v_and_b32_e32 v137, 0xffff0000, v134
	v_lshlrev_b32_e32 v134, 16, v135
	v_and_b32_e32 v135, 0xffff0000, v135
	v_lshlrev_b32_e32 v146, 16, v0
	v_and_b32_e32 v147, 0xffff0000, v0
	v_lshlrev_b32_e32 v144, 16, v145
	v_and_b32_e32 v145, 0xffff0000, v145
	v_pk_add_f32 v[134:135], v[76:77], v[134:135]
	v_pk_add_f32 v[136:137], v[74:75], v[136:137]
	v_cvt_pk_bf16_f32 v149, v134, v135
	v_pk_add_f32 v[144:145], v[68:69], v[144:145]
	s_waitcnt lgkmcnt(0)
	v_cvt_pk_bf16_f32 v148, v136, v137
	v_pk_add_f32 v[146:147], v[66:67], v[146:147]
	v_cvt_pk_bf16_f32 v151, v144, v145
	v_mov_b32_e32 v0, v132
	v_cvt_pk_bf16_f32 v150, v146, v147
	v_permlane16_swap_b32_e32 v149, v151
	v_permlane16_swap_b32_e32 v148, v150
	global_store_dwordx4 v[156:157], v[148:151], off
	v_permlane16_swap_b32_e32 v130, v0
	s_nop 0
	v_mov_b32_e32 v149, v133
	s_nop 1
	v_permlane16_swap_b32_e32 v131, v149
	v_lshlrev_b32_e32 v132, 16, v130
	v_and_b32_e32 v133, 0xffff0000, v130
	v_lshlrev_b32_e32 v130, 16, v131
	v_and_b32_e32 v131, 0xffff0000, v131
	v_lshlrev_b32_e32 v150, 16, v0
	v_and_b32_e32 v151, 0xffff0000, v0
	v_lshlrev_b32_e32 v148, 16, v149
	v_and_b32_e32 v149, 0xffff0000, v149
	v_pk_add_f32 v[130:131], v[80:81], v[130:131]
	v_pk_add_f32 v[132:133], v[78:79], v[132:133]
	v_cvt_pk_bf16_f32 v153, v130, v131
	v_pk_add_f32 v[148:149], v[72:73], v[148:149]
	v_cvt_pk_bf16_f32 v152, v132, v133
	v_pk_add_f32 v[150:151], v[70:71], v[150:151]
	v_cvt_pk_bf16_f32 v155, v148, v149
	s_and_b64 vcc, exec, s[10:11]
	v_cvt_pk_bf16_f32 v154, v150, v151
	v_permlane16_swap_b32_e32 v153, v155
	v_permlane16_swap_b32_e32 v152, v154
	global_store_dwordx4 v[156:157], v[152:155], off offset:256
	s_cbranch_vccnz .LBB0_867
	v_mul_f32_e32 v0, v137, v137
	v_mul_f32_e32 v135, v135, v135
	v_fmac_f32_e32 v0, v136, v136
	v_fmac_f32_e32 v135, v134, v134
	v_add_f32_e32 v0, v0, v135
	v_mul_f32_e32 v134, v147, v147
	v_mul_f32_e32 v135, v145, v145
	v_fmac_f32_e32 v134, v146, v146
	v_fmac_f32_e32 v135, v144, v144
	v_mul_f32_e32 v133, v133, v133
	v_mul_f32_e32 v131, v131, v131
	v_add_f32_e32 v134, v134, v135
	v_fmac_f32_e32 v133, v132, v132
	v_fmac_f32_e32 v131, v130, v130
	v_add_f32_e32 v0, v0, v134
	v_add_f32_e32 v130, v133, v131
	v_add_f32_e32 v0, v0, v130
	v_mul_f32_e32 v130, v151, v151
	v_mul_f32_e32 v131, v149, v149
	v_fmac_f32_e32 v130, v150, v150
	v_fmac_f32_e32 v131, v148, v148
	v_add_f32_e32 v130, v130, v131
	v_add_f32_e32 v0, v130, v0
	ds_bpermute_b32 v130, v241, v0
	s_waitcnt lgkmcnt(0)
	v_add_f32_e32 v0, v0, v130
	ds_bpermute_b32 v130, v242, v0
	s_and_saveexec_b64 s[0:1], s[6:7]
	s_cbranch_execz .LBB0_866
	s_waitcnt lgkmcnt(0)
	v_add_f32_e32 v0, v0, v130
	v_lshl_add_u64 v[130:131], s[38:39], 0, v[142:143]
	v_readlane_b32 s18, v252, 23
	s_lshl_b32 s2, s87, 2
	v_lshlrev_b64 v[130:131], 6, v[130:131]
	v_readlane_b32 s19, v252, 24
	s_ashr_i32 s3, s2, 31
	s_lshl_b32 s94, s65, 2
	v_lshl_add_u64 v[130:131], s[18:19], 0, v[130:131]
	v_lshl_add_u64 v[130:131], s[2:3], 2, v[130:131]
	v_lshl_add_u64 v[130:131], v[130:131], 0, s[94:95]
	global_store_dword v[130:131], v0, off

; __device__ __forceinline__ unsigned cvt_pk_bf16(float lo, float hi) { unsigned r; asm("v_cvt_pk_bf16_f32 %0, %1, %2" : "=v"(r) : "v"(lo), "v"(hi)); return r; }
;     __device__ __forceinline__ void operator()(const f32x4 (&acc)[2][2][4][2], const Unit& u, int wr, int wc, int fr, int fq) const {
;     ...
;             for (int am = 0; am < 4; ++am) { const int ai = am >> 1, mb = (am & 1) * 2;
;                 v4u xv[2][2];
; #pragma unroll
;                 for (int mm = 0; mm < 2; ++mm) { const int m = mb + mm; const bf16* rp = (const bf16*)(ws + WS_XB) + (size_t)(row0 + ai * 128 + m * 16) * D + colw;
; #pragma unroll
;                     for (int bj = 0; bj < 2; ++bj) xv[mm][bj] = *(const v4u*)(rp + bj * 128); }
; #pragma unroll
;                 for (int mm = 0; mm < 2; ++mm) { const int m = mb + mm;
;                     const int row = row0 + ai * 128 + m * 16;
;                     bf16* xb = (bf16*)(ws + WS_XB) + (size_t)row * D + colw;
;                     float ssq = 0.f;
; #pragma unroll
;                     for (int bj = 0; bj < 2; ++bj) {
;                         const auto s0 = __builtin_amdgcn_permlane16_swap(xv[mm][bj].x, xv[mm][bj].z, false, false), s1 = __builtin_amdgcn_permlane16_swap(xv[mm][bj].y, xv[mm][bj].w, false, false);
;                         const unsigned xn[2][2] = {{s0[0], s1[0]}, {s0[1], s1[1]}};
;                         unsigned wn[2][2];
; #pragma unroll
;                         for (int n = 0; n < 2; ++n) {
;                             const f32x4 v = (f32x4){bf_lo(xn[n][0]), bf_hi(xn[n][0]), bf_lo(xn[n][1]), bf_hi(xn[n][1])} + acc[ai][bj][m][n] * amul;
;                             wn[n][0] = cvt_pk_bf16(v.x, v.y); wn[n][1] = cvt_pk_bf16(v.z, v.w);
;                             if (slot >= 0) ssq += (v.x * v.x + v.y * v.y) + (v.z * v.z + v.w * v.w); }
;                         const auto t0 = __builtin_amdgcn_permlane16_swap(wn[0][0], wn[1][0], false, false), t1 = __builtin_amdgcn_permlane16_swap(wn[0][1], wn[1][1], false, false);
;                         *(v4u*)(xb + bj * 128) = (v4u){t0[0], t1[0], t0[1], t1[1]};
;                     }
;                     if (slot >= 0) { ssq += shfl_xor_l(ssq, 16, fq * 16 + fr); ssq += shfl_xor_l(ssq, 32, fq * 16 + fr); if (fq == 0) ((float*)(ws + WS_SS))[((size_t)slot * M + row) * 16 + u.pn * 4 + wc] = ssq; }
.LBB0_867:
	v_add_u32_e32 v146, 0x80, v210
	v_ashrrev_i32_e32 v147, 31, v146
	v_lshlrev_b64 v[152:153], 11, v[146:147]
	s_waitcnt lgkmcnt(0)
	v_lshl_add_u64 v[130:131], v[140:141], 0, v[152:153]
	v_add_u32_e32 v142, 0x90, v210
	v_ashrrev_i32_e32 v143, 31, v142
	v_lshlrev_b64 v[144:145], 11, v[142:143]
	v_lshl_add_u64 v[130:131], v[140:141], 0, v[144:145]
	s_nop 0
	v_lshl_add_u64 v[152:153], s[90:91], 0, v[152:153]
	v_lshl_add_u64 v[168:169], v[138:139], 1, v[152:153]
	s_and_b64 vcc, exec, s[10:11]
	s_waitcnt vmcnt(12)
	v_mov_b32_e32 v148, v204
	v_mov_b32_e32 v149, v205
	v_mov_b32_e32 v150, v206
	v_mov_b32_e32 v151, v207
	v_mov_b32_e32 v156, v212
	v_mov_b32_e32 v157, v213
	v_mov_b32_e32 v158, v214
	v_mov_b32_e32 v159, v215
	v_mov_b32_e32 v134, v216
	v_mov_b32_e32 v135, v217
	v_mov_b32_e32 v136, v218
	v_mov_b32_e32 v137, v219
	v_mov_b32_e32 v130, v246
	v_mov_b32_e32 v131, v247
	v_mov_b32_e32 v132, v248
	v_mov_b32_e32 v133, v249
	v_mov_b32_e32 v0, v150
	s_nop 1
	v_permlane16_swap_b32_e32 v148, v0
	v_mov_b32_e32 v162, v151
	s_nop 1
	v_permlane16_swap_b32_e32 v149, v162
	v_lshlrev_b32_e32 v150, 16, v148
	v_and_b32_e32 v151, 0xffff0000, v148
	v_lshlrev_b32_e32 v148, 16, v149
	v_and_b32_e32 v149, 0xffff0000, v149
	v_pk_add_f32 v[152:153], v[58:59], v[150:151]
	v_lshlrev_b32_e32 v154, 16, v0
	v_and_b32_e32 v155, 0xffff0000, v0
	v_lshlrev_b32_e32 v150, 16, v162
	v_and_b32_e32 v151, 0xffff0000, v162
	v_mov_b32_e32 v0, v158
	v_pk_add_f32 v[148:149], v[60:61], v[148:149]
	v_cvt_pk_bf16_f32 v160, v152, v153
	v_pk_add_f32 v[150:151], v[52:53], v[150:151]
	v_cvt_pk_bf16_f32 v161, v148, v149
	v_pk_add_f32 v[154:155], v[50:51], v[154:155]
	v_cvt_pk_bf16_f32 v163, v150, v151
	v_permlane16_swap_b32_e32 v156, v0
	v_cvt_pk_bf16_f32 v162, v154, v155
	v_mov_b32_e32 v166, v159
	v_permlane16_swap_b32_e32 v160, v162
	v_permlane16_swap_b32_e32 v161, v163
	v_permlane16_swap_b32_e32 v157, v166
	v_lshlrev_b32_e32 v158, 16, v156
	v_and_b32_e32 v159, 0xffff0000, v156
	global_store_dwordx4 v[168:169], v[160:163], off
	v_lshlrev_b32_e32 v156, 16, v157
	v_and_b32_e32 v157, 0xffff0000, v157
	v_pk_add_f32 v[160:161], v[62:63], v[158:159]
	v_lshlrev_b32_e32 v162, 16, v0
	v_and_b32_e32 v163, 0xffff0000, v0
	v_lshlrev_b32_e32 v158, 16, v166
	v_and_b32_e32 v159, 0xffff0000, v166
	v_pk_add_f32 v[156:157], v[64:65], v[156:157]
	v_cvt_pk_bf16_f32 v164, v160, v161
	v_pk_add_f32 v[158:159], v[56:57], v[158:159]
	v_cvt_pk_bf16_f32 v165, v156, v157
	v_pk_add_f32 v[162:163], v[54:55], v[162:163]
	v_cvt_pk_bf16_f32 v167, v158, v159
	s_nop 0
	v_cvt_pk_bf16_f32 v166, v162, v163
	v_permlane16_swap_b32_e32 v165, v167
	v_permlane16_swap_b32_e32 v164, v166
	global_store_dwordx4 v[168:169], v[164:167], off offset:256
	s_cbranch_vccnz .LBB0_871
	v_mul_f32_e32 v0, v153, v153
	v_mul_f32_e32 v149, v149, v149
	v_fmac_f32_e32 v0, v152, v152
	v_fmac_f32_e32 v149, v148, v148
	v_add_f32_e32 v0, v0, v149
	v_mul_f32_e32 v148, v155, v155
	v_mul_f32_e32 v149, v151, v151
	v_fmac_f32_e32 v148, v154, v154
	v_fmac_f32_e32 v149, v150, v150
	v_add_f32_e32 v148, v148, v149
	v_add_f32_e32 v0, v0, v148
	v_mul_f32_e32 v148, v161, v161
	v_mul_f32_e32 v149, v157, v157
	v_fmac_f32_e32 v148, v160, v160
	v_fmac_f32_e32 v149, v156, v156
	v_add_f32_e32 v148, v148, v149
	v_add_f32_e32 v0, v0, v148
	v_mul_f32_e32 v148, v163, v163
	v_mul_f32_e32 v149, v159, v159
	v_fmac_f32_e32 v148, v162, v162
	v_fmac_f32_e32 v149, v158, v158
	v_add_f32_e32 v148, v148, v149
	v_add_f32_e32 v0, v148, v0
	ds_bpermute_b32 v148, v241, v0
	s_waitcnt lgkmcnt(0)
	v_add_f32_e32 v0, v0, v148
	ds_bpermute_b32 v148, v242, v0
	s_and_saveexec_b64 s[0:1], s[6:7]
	s_cbranch_execz .LBB0_870
	v_lshl_add_u64 v[146:147], s[38:39], 0, v[146:147]
	v_readlane_b32 s18, v252, 23
	s_lshl_b32 s2, s87, 2
	v_lshlrev_b64 v[146:147], 6, v[146:147]
	v_readlane_b32 s19, v252, 24
	s_ashr_i32 s3, s2, 31
	s_lshl_b32 s94, s65, 2
	v_lshl_add_u64 v[146:147], s[18:19], 0, v[146:147]
	v_lshl_add_u64 v[146:147], s[2:3], 2, v[146:147]
	s_waitcnt lgkmcnt(0)
	v_add_f32_e32 v0, v0, v148
	v_lshl_add_u64 v[146:147], v[146:147], 0, s[94:95]
	global_store_dword v[146:147], v0, off

; __device__ __forceinline__ unsigned cvt_pk_bf16(float lo, float hi) { unsigned r; asm("v_cvt_pk_bf16_f32 %0, %1, %2" : "=v"(r) : "v"(lo), "v"(hi)); return r; }
; __device__ __forceinline__ float bf_lo(unsigned w) { return __uint_as_float(w << 16); }
; __device__ __forceinline__ float bf_hi(unsigned w) { return __uint_as_float(w & 0xffff0000u); }
; __device__ __forceinline__ float shfl_xor_l(float v, int m, int lane) { return __int_as_float(__builtin_amdgcn_ds_bpermute((lane ^ m) << 2, __float_as_int(v))); }
;     __device__ __forceinline__ void operator()(const f32x4 (&acc)[2][2][4][2], const Unit& u, int wr, int wc, int fr, int fq) const {
;     ...
;                 for (int mm = 0; mm < 2; ++mm) { const int m = mb + mm;
;                     const int row = row0 + ai * 128 + m * 16;
;                     bf16* xb = (bf16*)(ws + WS_XB) + (size_t)row * D + colw;
;                     float ssq = 0.f;
; #pragma unroll
;                     for (int bj = 0; bj < 2; ++bj) {
;                         const auto s0 = __builtin_amdgcn_permlane16_swap(xv[mm][bj].x, xv[mm][bj].z, false, false), s1 = __builtin_amdgcn_permlane16_swap(xv[mm][bj].y, xv[mm][bj].w, false, false);
;                         const unsigned xn[2][2] = {{s0[0], s1[0]}, {s0[1], s1[1]}};
;                         unsigned wn[2][2];
; #pragma unroll
;                         for (int n = 0; n < 2; ++n) {
;                             const f32x4 v = (f32x4){bf_lo(xn[n][0]), bf_hi(xn[n][0]), bf_lo(xn[n][1]), bf_hi(xn[n][1])} + acc[ai][bj][m][n] * amul;
;                             wn[n][0] = cvt_pk_bf16(v.x, v.y); wn[n][1] = cvt_pk_bf16(v.z, v.w);
;                             if (slot >= 0) ssq += (v.x * v.x + v.y * v.y) + (v.z * v.z + v.w * v.w); }
;                         const auto t0 = __builtin_amdgcn_permlane16_swap(wn[0][0], wn[1][0], false, false), t1 = __builtin_amdgcn_permlane16_swap(wn[0][1], wn[1][1], false, false);
;                         *(v4u*)(xb + bj * 128) = (v4u){t0[0], t1[0], t0[1], t1[1]};
;                     }
;                     if (slot >= 0) { ssq += shfl_xor_l(ssq, 16, fq * 16 + fr); ssq += shfl_xor_l(ssq, 32, fq * 16 + fr); if (fq == 0) ((float*)(ws + WS_SS))[((size_t)slot * M + row) * 16 + u.pn * 4 + wc] = ssq; }
.LBB0_871:
	v_lshl_add_u64 v[144:145], s[90:91], 0, v[144:145]
	v_lshl_add_u64 v[156:157], v[138:139], 1, v[144:145]
	v_mov_b32_e32 v0, v136
	v_mov_b32_e32 v145, v137
	s_nop 0
	v_permlane16_swap_b32_e32 v134, v0
	v_permlane16_swap_b32_e32 v135, v145
	v_lshlrev_b32_e32 v136, 16, v134
	v_and_b32_e32 v137, 0xffff0000, v134
	v_lshlrev_b32_e32 v134, 16, v135
	v_and_b32_e32 v135, 0xffff0000, v135
	v_lshlrev_b32_e32 v146, 16, v0
	v_and_b32_e32 v147, 0xffff0000, v0
	v_lshlrev_b32_e32 v144, 16, v145
	v_and_b32_e32 v145, 0xffff0000, v145
	v_pk_add_f32 v[134:135], v[44:45], v[134:135]
	v_pk_add_f32 v[136:137], v[42:43], v[136:137]
	v_cvt_pk_bf16_f32 v149, v134, v135
	v_pk_add_f32 v[144:145], v[36:37], v[144:145]
	s_waitcnt lgkmcnt(0)
	v_cvt_pk_bf16_f32 v148, v136, v137
	v_pk_add_f32 v[146:147], v[34:35], v[146:147]
	v_cvt_pk_bf16_f32 v151, v144, v145
	v_mov_b32_e32 v0, v132
	v_cvt_pk_bf16_f32 v150, v146, v147
	v_permlane16_swap_b32_e32 v149, v151
	v_permlane16_swap_b32_e32 v148, v150
	global_store_dwordx4 v[156:157], v[148:151], off
	v_permlane16_swap_b32_e32 v130, v0
	s_nop 0
	v_mov_b32_e32 v149, v133
	s_nop 1
	v_permlane16_swap_b32_e32 v131, v149
	v_lshlrev_b32_e32 v132, 16, v130
	v_and_b32_e32 v133, 0xffff0000, v130
	v_lshlrev_b32_e32 v130, 16, v131
	v_and_b32_e32 v131, 0xffff0000, v131
	v_lshlrev_b32_e32 v150, 16, v0
	v_and_b32_e32 v151, 0xffff0000, v0
	v_lshlrev_b32_e32 v148, 16, v149
	v_and_b32_e32 v149, 0xffff0000, v149
	v_pk_add_f32 v[130:131], v[48:49], v[130:131]
	v_pk_add_f32 v[132:133], v[46:47], v[132:133]
	v_cvt_pk_bf16_f32 v153, v130, v131
	v_pk_add_f32 v[148:149], v[40:41], v[148:149]
	v_cvt_pk_bf16_f32 v152, v132, v133
	v_pk_add_f32 v[150:151], v[38:39], v[150:151]
	v_cvt_pk_bf16_f32 v155, v148, v149
	s_and_b64 vcc, exec, s[10:11]
	v_cvt_pk_bf16_f32 v154, v150, v151
	v_permlane16_swap_b32_e32 v153, v155
	v_permlane16_swap_b32_e32 v152, v154
	global_store_dwordx4 v[156:157], v[152:155], off offset:256
	s_cbranch_vccnz .LBB0_875
	v_mul_f32_e32 v0, v137, v137
	v_mul_f32_e32 v135, v135, v135
	v_fmac_f32_e32 v0, v136, v136
	v_fmac_f32_e32 v135, v134, v134
	v_add_f32_e32 v0, v0, v135
	v_mul_f32_e32 v134, v147, v147
	v_mul_f32_e32 v135, v145, v145
	v_fmac_f32_e32 v134, v146, v146
	v_fmac_f32_e32 v135, v144, v144
	v_mul_f32_e32 v133, v133, v133
	v_mul_f32_e32 v131, v131, v131
	v_add_f32_e32 v134, v134, v135
	v_fmac_f32_e32 v133, v132, v132
	v_fmac_f32_e32 v131, v130, v130
	v_add_f32_e32 v0, v0, v134
	v_add_f32_e32 v130, v133, v131
	v_add_f32_e32 v0, v0, v130
	v_mul_f32_e32 v130, v151, v151
	v_mul_f32_e32 v131, v149, v149
	v_fmac_f32_e32 v130, v150, v150
	v_fmac_f32_e32 v131, v148, v148
	v_add_f32_e32 v130, v130, v131
	v_add_f32_e32 v0, v130, v0
	ds_bpermute_b32 v130, v241, v0
	s_waitcnt lgkmcnt(0)
	v_add_f32_e32 v0, v0, v130
	ds_bpermute_b32 v130, v242, v0
	s_and_saveexec_b64 s[0:1], s[6:7]
	s_cbranch_execz .LBB0_874
	s_waitcnt lgkmcnt(0)
	v_add_f32_e32 v0, v0, v130
	v_lshl_add_u64 v[130:131], s[38:39], 0, v[142:143]
	v_readlane_b32 s18, v252, 23
	s_lshl_b32 s2, s87, 2
	v_lshlrev_b64 v[130:131], 6, v[130:131]
	v_readlane_b32 s19, v252, 24
	s_ashr_i32 s3, s2, 31
	s_lshl_b32 s94, s65, 2
	v_lshl_add_u64 v[130:131], s[18:19], 0, v[130:131]
	v_lshl_add_u64 v[130:131], s[2:3], 2, v[130:131]
	v_lshl_add_u64 v[130:131], v[130:131], 0, s[94:95]
	global_store_dword v[130:131], v0, off

; __device__ __forceinline__ unsigned cvt_pk_bf16(float lo, float hi) { unsigned r; asm("v_cvt_pk_bf16_f32 %0, %1, %2" : "=v"(r) : "v"(lo), "v"(hi)); return r; }
;     __device__ __forceinline__ void operator()(const f32x4 (&acc)[2][2][4][2], const Unit& u, int wr, int wc, int fr, int fq) const {
;     ...
;             for (int am = 0; am < 4; ++am) { const int ai = am >> 1, mb = (am & 1) * 2;
;                 v4u xv[2][2];
; #pragma unroll
;                 for (int mm = 0; mm < 2; ++mm) { const int m = mb + mm; const bf16* rp = (const bf16*)(ws + WS_XB) + (size_t)(row0 + ai * 128 + m * 16) * D + colw;
; #pragma unroll
;                     for (int bj = 0; bj < 2; ++bj) xv[mm][bj] = *(const v4u*)(rp + bj * 128); }
; #pragma unroll
;                 for (int mm = 0; mm < 2; ++mm) { const int m = mb + mm;
;                     const int row = row0 + ai * 128 + m * 16;
;                     bf16* xb = (bf16*)(ws + WS_XB) + (size_t)row * D + colw;
;                     float ssq = 0.f;
; #pragma unroll
;                     for (int bj = 0; bj < 2; ++bj) {
;                         const auto s0 = __builtin_amdgcn_permlane16_swap(xv[mm][bj].x, xv[mm][bj].z, false, false), s1 = __builtin_amdgcn_permlane16_swap(xv[mm][bj].y, xv[mm][bj].w, false, false);
;                         const unsigned xn[2][2] = {{s0[0], s1[0]}, {s0[1], s1[1]}};
;                         unsigned wn[2][2];
; #pragma unroll
;                         for (int n = 0; n < 2; ++n) {
;                             const f32x4 v = (f32x4){bf_lo(xn[n][0]), bf_hi(xn[n][0]), bf_lo(xn[n][1]), bf_hi(xn[n][1])} + acc[ai][bj][m][n] * amul;
;                             wn[n][0] = cvt_pk_bf16(v.x, v.y); wn[n][1] = cvt_pk_bf16(v.z, v.w);
;                             if (slot >= 0) ssq += (v.x * v.x + v.y * v.y) + (v.z * v.z + v.w * v.w); }
;                         const auto t0 = __builtin_amdgcn_permlane16_swap(wn[0][0], wn[1][0], false, false), t1 = __builtin_amdgcn_permlane16_swap(wn[0][1], wn[1][1], false, false);
;                         *(v4u*)(xb + bj * 128) = (v4u){t0[0], t1[0], t0[1], t1[1]};
;                     }
;                     if (slot >= 0) { ssq += shfl_xor_l(ssq, 16, fq * 16 + fr); ssq += shfl_xor_l(ssq, 32, fq * 16 + fr); if (fq == 0) ((float*)(ws + WS_SS))[((size_t)slot * M + row) * 16 + u.pn * 4 + wc] = ssq; }
.LBB0_875:
	v_add_u32_e32 v146, 0xa0, v210
	v_ashrrev_i32_e32 v147, 31, v146
	v_lshlrev_b64 v[152:153], 11, v[146:147]
	s_waitcnt lgkmcnt(0)
	v_lshl_add_u64 v[130:131], v[140:141], 0, v[152:153]
	v_add_u32_e32 v142, 0xb0, v210
	v_ashrrev_i32_e32 v143, 31, v142
	v_lshlrev_b64 v[144:145], 11, v[142:143]
	v_lshl_add_u64 v[130:131], v[140:141], 0, v[144:145]
	s_nop 0
	v_lshl_add_u64 v[140:141], s[90:91], 0, v[152:153]
	v_lshl_add_u64 v[166:167], v[138:139], 1, v[140:141]
	s_and_b64 vcc, exec, s[10:11]
	s_waitcnt vmcnt(8)
	v_mov_b32_e32 v148, v170
	v_mov_b32_e32 v149, v171
	v_mov_b32_e32 v150, v172
	v_mov_b32_e32 v151, v173
	v_mov_b32_e32 v154, v174
	v_mov_b32_e32 v155, v175
	v_mov_b32_e32 v156, v176
	v_mov_b32_e32 v157, v177
	v_mov_b32_e32 v134, v178
	v_mov_b32_e32 v135, v179
	v_mov_b32_e32 v136, v180
	v_mov_b32_e32 v137, v181
	v_mov_b32_e32 v130, v182
	v_mov_b32_e32 v131, v183
	v_mov_b32_e32 v132, v184
	v_mov_b32_e32 v133, v185
	v_mov_b32_e32 v0, v150
	v_mov_b32_e32 v160, v151
	s_nop 0
	v_permlane16_swap_b32_e32 v148, v0
	v_permlane16_swap_b32_e32 v149, v160
	v_lshlrev_b32_e32 v150, 16, v148
	v_and_b32_e32 v151, 0xffff0000, v148
	v_lshlrev_b32_e32 v140, 16, v149
	v_and_b32_e32 v141, 0xffff0000, v149
	v_lshlrev_b32_e32 v152, 16, v0
	v_and_b32_e32 v153, 0xffff0000, v0
	v_lshlrev_b32_e32 v148, 16, v160
	v_and_b32_e32 v149, 0xffff0000, v160
	v_mov_b32_e32 v0, v156
	v_pk_add_f32 v[140:141], v[28:29], v[140:141]
	v_pk_add_f32 v[150:151], v[26:27], v[150:151]
	v_cvt_pk_bf16_f32 v159, v140, v141
	v_pk_add_f32 v[148:149], v[20:21], v[148:149]
	v_cvt_pk_bf16_f32 v158, v150, v151
	v_pk_add_f32 v[152:153], v[18:19], v[152:153]
	v_cvt_pk_bf16_f32 v161, v148, v149
	v_permlane16_swap_b32_e32 v154, v0
	v_cvt_pk_bf16_f32 v160, v152, v153
	v_mov_b32_e32 v164, v157
	v_permlane16_swap_b32_e32 v158, v160
	v_permlane16_swap_b32_e32 v159, v161
	v_permlane16_swap_b32_e32 v155, v164
	v_lshlrev_b32_e32 v156, 16, v154
	v_and_b32_e32 v157, 0xffff0000, v154
	global_store_dwordx4 v[166:167], v[158:161], off
	v_lshlrev_b32_e32 v154, 16, v155
	v_and_b32_e32 v155, 0xffff0000, v155
	v_pk_add_f32 v[158:159], v[30:31], v[156:157]
	v_lshlrev_b32_e32 v160, 16, v0
	v_and_b32_e32 v161, 0xffff0000, v0
	v_lshlrev_b32_e32 v156, 16, v164
	v_and_b32_e32 v157, 0xffff0000, v164
	v_pk_add_f32 v[154:155], v[32:33], v[154:155]
	v_cvt_pk_bf16_f32 v162, v158, v159
	v_pk_add_f32 v[156:157], v[24:25], v[156:157]
	v_cvt_pk_bf16_f32 v163, v154, v155
	v_pk_add_f32 v[160:161], v[22:23], v[160:161]
	v_cvt_pk_bf16_f32 v165, v156, v157
	s_nop 0
	v_cvt_pk_bf16_f32 v164, v160, v161
	v_permlane16_swap_b32_e32 v163, v165
	v_permlane16_swap_b32_e32 v162, v164
	global_store_dwordx4 v[166:167], v[162:165], off offset:256
	s_cbranch_vccnz .LBB0_879
	v_mul_f32_e32 v0, v151, v151
	v_mul_f32_e32 v141, v141, v141
	v_fmac_f32_e32 v0, v150, v150
	v_fmac_f32_e32 v141, v140, v140
	v_add_f32_e32 v0, v0, v141
	v_mul_f32_e32 v140, v153, v153
	v_mul_f32_e32 v141, v149, v149
	v_fmac_f32_e32 v140, v152, v152
	v_fmac_f32_e32 v141, v148, v148
	v_add_f32_e32 v140, v140, v141
	v_add_f32_e32 v0, v0, v140
	v_mul_f32_e32 v140, v159, v159
	v_mul_f32_e32 v141, v155, v155
	v_fmac_f32_e32 v140, v158, v158
	v_fmac_f32_e32 v141, v154, v154
	v_add_f32_e32 v140, v140, v141
	v_add_f32_e32 v0, v0, v140
	v_mul_f32_e32 v140, v161, v161
	v_mul_f32_e32 v141, v157, v157
	v_fmac_f32_e32 v140, v160, v160
	v_fmac_f32_e32 v141, v156, v156
	v_add_f32_e32 v140, v140, v141
	v_add_f32_e32 v0, v140, v0
	ds_bpermute_b32 v140, v241, v0
	s_waitcnt lgkmcnt(0)
	v_add_f32_e32 v0, v0, v140
	ds_bpermute_b32 v140, v242, v0
	s_and_saveexec_b64 s[0:1], s[6:7]
	s_cbranch_execz .LBB0_878
	s_waitcnt lgkmcnt(0)
	v_add_f32_e32 v0, v0, v140
	v_lshl_add_u64 v[140:141], s[38:39], 0, v[146:147]
	v_readlane_b32 s18, v252, 23
	s_lshl_b32 s2, s87, 2
	v_lshlrev_b64 v[140:141], 6, v[140:141]
	v_readlane_b32 s19, v252, 24
	s_ashr_i32 s3, s2, 31
	s_lshl_b32 s94, s65, 2
	v_lshl_add_u64 v[140:141], s[18:19], 0, v[140:141]
	v_lshl_add_u64 v[140:141], s[2:3], 2, v[140:141]
	v_lshl_add_u64 v[140:141], v[140:141], 0, s[94:95]
	global_store_dword v[140:141], v0, off

; __device__ __forceinline__ unsigned cvt_pk_bf16(float lo, float hi) { unsigned r; asm("v_cvt_pk_bf16_f32 %0, %1, %2" : "=v"(r) : "v"(lo), "v"(hi)); return r; }
;     __device__ __forceinline__ void operator()(const f32x4 (&acc)[2][2][4][2], const Unit& u, int wr, int wc, int fr, int fq) const {
;     ...
;             for (int am = 0; am < 4; ++am) { const int ai = am >> 1, mb = (am & 1) * 2;
;                 v4u xv[2][2];
; #pragma unroll
;                 for (int mm = 0; mm < 2; ++mm) { const int m = mb + mm; const bf16* rp = (const bf16*)(ws + WS_XB) + (size_t)(row0 + ai * 128 + m * 16) * D + colw;
; #pragma unroll
;                     for (int bj = 0; bj < 2; ++bj) xv[mm][bj] = *(const v4u*)(rp + bj * 128); }
; #pragma unroll
;                 for (int mm = 0; mm < 2; ++mm) { const int m = mb + mm;
;                     const int row = row0 + ai * 128 + m * 16;
;                     bf16* xb = (bf16*)(ws + WS_XB) + (size_t)row * D + colw;
;                     float ssq = 0.f;
; #pragma unroll
;                     for (int bj = 0; bj < 2; ++bj) {
;                         const auto s0 = __builtin_amdgcn_permlane16_swap(xv[mm][bj].x, xv[mm][bj].z, false, false), s1 = __builtin_amdgcn_permlane16_swap(xv[mm][bj].y, xv[mm][bj].w, false, false);
;                         const unsigned xn[2][2] = {{s0[0], s1[0]}, {s0[1], s1[1]}};
;                         unsigned wn[2][2];
; #pragma unroll
;                         for (int n = 0; n < 2; ++n) {
;                             const f32x4 v = (f32x4){bf_lo(xn[n][0]), bf_hi(xn[n][0]), bf_lo(xn[n][1]), bf_hi(xn[n][1])} + acc[ai][bj][m][n] * amul;
;                             wn[n][0] = cvt_pk_bf16(v.x, v.y); wn[n][1] = cvt_pk_bf16(v.z, v.w);
;                             if (slot >= 0) ssq += (v.x * v.x + v.y * v.y) + (v.z * v.z + v.w * v.w); }
;                         const auto t0 = __builtin_amdgcn_permlane16_swap(wn[0][0], wn[1][0], false, false), t1 = __builtin_amdgcn_permlane16_swap(wn[0][1], wn[1][1], false, false);
;                         *(v4u*)(xb + bj * 128) = (v4u){t0[0], t1[0], t0[1], t1[1]};
;                     }
;                     if (slot >= 0) { ssq += shfl_xor_l(ssq, 16, fq * 16 + fr); ssq += shfl_xor_l(ssq, 32, fq * 16 + fr); if (fq == 0) ((float*)(ws + WS_SS))[((size_t)slot * M + row) * 16 + u.pn * 4 + wc] = ssq; }
;                 }
.LBB0_879:
	s_waitcnt lgkmcnt(0)
	v_lshl_add_u64 v[140:141], s[90:91], 0, v[144:145]
	v_lshl_add_u64 v[152:153], v[138:139], 1, v[140:141]
	v_mov_b32_e32 v0, v136
	v_mov_b32_e32 v139, v137
	s_nop 0
	v_permlane16_swap_b32_e32 v134, v0
	v_permlane16_swap_b32_e32 v135, v139
	v_lshlrev_b32_e32 v136, 16, v134
	v_and_b32_e32 v137, 0xffff0000, v134
	v_lshlrev_b32_e32 v134, 16, v135
	v_and_b32_e32 v135, 0xffff0000, v135
	v_lshlrev_b32_e32 v140, 16, v0
	v_and_b32_e32 v141, 0xffff0000, v0
	v_lshlrev_b32_e32 v138, 16, v139
	v_and_b32_e32 v139, 0xffff0000, v139
	v_pk_add_f32 v[134:135], v[12:13], v[134:135]
	v_pk_add_f32 v[136:137], v[10:11], v[136:137]
	v_cvt_pk_bf16_f32 v145, v134, v135
	v_pk_add_f32 v[138:139], v[8:9], v[138:139]
	v_cvt_pk_bf16_f32 v144, v136, v137
	v_pk_add_f32 v[140:141], v[6:7], v[140:141]
	v_cvt_pk_bf16_f32 v147, v138, v139
	v_mov_b32_e32 v0, v132
	v_cvt_pk_bf16_f32 v146, v140, v141
	v_permlane16_swap_b32_e32 v145, v147
	v_permlane16_swap_b32_e32 v144, v146
	global_store_dwordx4 v[152:153], v[144:147], off
	v_permlane16_swap_b32_e32 v130, v0
	s_nop 0
	v_mov_b32_e32 v145, v133
	s_nop 1
	v_permlane16_swap_b32_e32 v131, v145
	v_lshlrev_b32_e32 v132, 16, v130
	v_and_b32_e32 v133, 0xffff0000, v130
	v_lshlrev_b32_e32 v130, 16, v131
	v_and_b32_e32 v131, 0xffff0000, v131
	v_lshlrev_b32_e32 v146, 16, v0
	v_and_b32_e32 v147, 0xffff0000, v0
	v_lshlrev_b32_e32 v144, 16, v145
	v_and_b32_e32 v145, 0xffff0000, v145
	v_pk_add_f32 v[130:131], v[16:17], v[130:131]
	v_pk_add_f32 v[132:133], v[14:15], v[132:133]
	v_cvt_pk_bf16_f32 v149, v130, v131
	v_pk_add_f32 v[144:145], v[4:5], v[144:145]
	v_cvt_pk_bf16_f32 v148, v132, v133
	v_pk_add_f32 v[146:147], v[2:3], v[146:147]
	v_cvt_pk_bf16_f32 v151, v144, v145
	s_and_b64 vcc, exec, s[10:11]
	v_cvt_pk_bf16_f32 v150, v146, v147
	v_permlane16_swap_b32_e32 v149, v151
	v_permlane16_swap_b32_e32 v148, v150
	global_store_dwordx4 v[152:153], v[148:151], off offset:256
	s_cbranch_vccnz .LBB0_883
	v_mul_f32_e32 v0, v137, v137
	v_mul_f32_e32 v135, v135, v135
	v_fmac_f32_e32 v0, v136, v136
	v_fmac_f32_e32 v135, v134, v134
	v_add_f32_e32 v0, v0, v135
	v_mul_f32_e32 v134, v141, v141
	v_mul_f32_e32 v135, v139, v139
	v_fmac_f32_e32 v134, v140, v140
	v_fmac_f32_e32 v135, v138, v138
	v_mul_f32_e32 v133, v133, v133
	v_mul_f32_e32 v131, v131, v131
	v_add_f32_e32 v134, v134, v135
	v_fmac_f32_e32 v133, v132, v132
	v_fmac_f32_e32 v131, v130, v130
	v_add_f32_e32 v0, v0, v134
	v_add_f32_e32 v130, v133, v131
	v_add_f32_e32 v0, v0, v130
	v_mul_f32_e32 v130, v147, v147
	v_mul_f32_e32 v131, v145, v145
	v_fmac_f32_e32 v130, v146, v146
	v_fmac_f32_e32 v131, v144, v144
	v_add_f32_e32 v130, v130, v131
	v_add_f32_e32 v0, v130, v0
	ds_bpermute_b32 v130, v241, v0
	s_waitcnt lgkmcnt(0)
	v_add_f32_e32 v0, v0, v130
	ds_bpermute_b32 v130, v242, v0
	s_and_saveexec_b64 s[0:1], s[6:7]
	s_cbranch_execz .LBB0_882
	s_waitcnt lgkmcnt(0)
	v_add_f32_e32 v0, v0, v130
	v_lshl_add_u64 v[130:131], s[38:39], 0, v[142:143]
	v_readlane_b32 s10, v252, 23
	s_lshl_b32 s2, s87, 2
	v_lshlrev_b64 v[130:131], 6, v[130:131]
	v_readlane_b32 s11, v252, 24
	s_ashr_i32 s3, s2, 31
	s_lshl_b32 s94, s65, 2
	v_lshl_add_u64 v[130:131], s[10:11], 0, v[130:131]
	v_lshl_add_u64 v[130:131], s[2:3], 2, v[130:131]
	v_lshl_add_u64 v[130:131], v[130:131], 0, s[94:95]
	global_store_dword v[130:131], v0, off
